# spatial-gating item: batch the eight row-sum butterfly reductions (40 dependent LDS-permute round trips -> 10), same arithmetic order
# speedup vs baseline: 1.0174x; 1.0079x over previous
.LBB0_714:
	s_or_b64 exec, exec, s[2:3]
	v_and_b32_e32 v63, 31, v55
	v_lshl_add_u32 v57, v63, 5, 0
	v_and_b32_e32 v50, 64, v217
	s_waitcnt lgkmcnt(0)
	s_barrier
	v_add_u32_e32 v69, 64, v50
	ds_read_b128 v[50:53], v57
	ds_read_b128 v[58:61], v57 offset:16
	v_lshlrev_b32_e32 v56, 2, v63
	v_ashrrev_i32_e32 v62, 5, v55
	v_cmp_ge_i32_e32 vcc, v62, v56
	s_movk_i32 s0, 0xffe8
	s_waitcnt vmcnt(7)
	v_cndmask_b32_e32 v65, 0, v46, vcc
	v_cmp_lt_i32_e32 vcc, v56, v62
	s_waitcnt lgkmcnt(1)
	v_mov_b32_e32 v46, v53
	v_cndmask_b32_e32 v64, 0, v47, vcc
	v_mov_b32_e32 v47, v51
	v_pk_mul_f32 v[46:47], v[64:65], v[46:47]
	s_nop 0
	v_and_b32_sdwa v51, v47, v221 dst_sel:DWORD dst_unused:UNUSED_PAD src0_sel:WORD_1 src1_sel:DWORD
	v_and_b32_sdwa v53, v46, v221 dst_sel:DWORD dst_unused:UNUSED_PAD src0_sel:WORD_1 src1_sel:DWORD
	v_add3_u32 v72, v47, v51, s23
	v_add3_u32 v46, v46, v53, s23
	v_or_b32_e32 v47, 3, v56
	v_and_b32_e32 v67, 0xffff0000, v46
	v_or_b32_e32 v46, 2, v56
	v_cmp_le_i32_e32 vcc, v47, v62
	v_and_b32_e32 v66, 0xffff0000, v72
	s_nop 0
	v_cndmask_b32_e32 v71, 0, v49, vcc
	v_cmp_le_i32_e32 vcc, v46, v62
	s_waitcnt lgkmcnt(0)
	v_mov_b32_e32 v49, v61
	v_cndmask_b32_e32 v70, 0, v48, vcc
	v_mov_b32_e32 v48, v59
	v_pk_mul_f32 v[48:49], v[70:71], v[48:49]
	s_nop 0
	v_and_b32_sdwa v51, v49, v221 dst_sel:DWORD dst_unused:UNUSED_PAD src0_sel:WORD_1 src1_sel:DWORD
	v_and_b32_sdwa v53, v48, v221 dst_sel:DWORD dst_unused:UNUSED_PAD src0_sel:WORD_1 src1_sel:DWORD
	v_add3_u32 v49, v49, v51, s23
	v_add3_u32 v73, v48, v53, s23
	v_mov_b32_e32 v51, v52
	v_mul_f32_e32 v48, v52, v67
	v_and_b32_e32 v74, 0xffff0000, v49
	v_pk_fma_f32 v[50:51], v[50:51], v[66:67], v[48:49] op_sel_hi:[1,1,0]
	v_and_b32_e32 v48, 0xffff0000, v73
	v_mov_b32_e32 v49, v64
	v_mul_f32_e32 v52, v58, v48
	v_mul_f32_e32 v58, v60, v74
	v_pk_add_f32 v[60:61], v[64:65], v[48:49]
	v_xor_b32_e32 v48, 1, v217
	v_cmp_lt_i32_e32 vcc, v48, v69
	v_mov_b32_e32 v51, v70
	v_mov_b32_e32 v53, v71
	v_cndmask_b32_e32 v48, v217, v48, vcc
	v_pk_add_f32 v[50:51], v[50:51], v[52:53]
	v_mov_b32_e32 v59, v61
	v_lshlrev_b32_e32 v49, 2, v48
	v_pk_add_f32 v[50:51], v[58:59], v[50:51]
	v_mov_b32_e32 v110, v50
	v_mov_b32_e32 v111, v51
	v_xor_b32_e32 v48, 2, v217
	v_cmp_lt_i32_e32 vcc, v48, v69
	v_or_b32_sdwa v64, v67, v72 dst_sel:DWORD dst_unused:UNUSED_PAD src0_sel:DWORD src1_sel:WORD_1
	v_or_b32_sdwa v65, v74, v73 dst_sel:DWORD dst_unused:UNUSED_PAD src0_sel:DWORD src1_sel:WORD_1
	v_cndmask_b32_e32 v48, v217, v48, vcc
	v_lshlrev_b32_e32 v58, 2, v48
	v_xor_b32_e32 v48, 4, v217
	v_cmp_lt_i32_e32 vcc, v48, v69
	v_cndmask_b32_e32 v48, v217, v48, vcc
	v_lshlrev_b32_e32 v59, 2, v48
	v_xor_b32_e32 v48, 8, v217
	v_cmp_lt_i32_e32 vcc, v48, v69
	v_cndmask_b32_e32 v48, v217, v48, vcc
	v_lshlrev_b32_e32 v60, 2, v48
	v_mad_i32_i24 v48, v63, s0, v57
	v_cmp_eq_u32_e32 vcc, 0, v63
	v_xor_b32_e32 v52, 16, v217
	v_cmp_lt_i32_e64 s[0:1], v52, v69
	s_nop 1
	v_cndmask_b32_e64 v52, v217, v52, s[0:1]
	v_lshlrev_b32_e32 v61, 2, v52
	v_mad_u64_u32 v[66:67], s[0:1], v62, s13, v[48:49]
	ds_write_b64 v66, v[64:65] offset:2048
	v_add_u32_e32 v50, 0x200, v55
	ds_read_b128 v[62:65], v57
	ds_read_b128 v[70:73], v57 offset:16
	v_ashrrev_i32_e32 v50, 5, v50
	v_cmp_ge_i32_e64 s[0:1], v50, v46
	s_waitcnt lgkmcnt(1)
	v_mov_b32_e32 v66, v63
	s_waitcnt vmcnt(6)
	v_cndmask_b32_e64 v53, 0, v44, s[0:1]
	v_cmp_lt_i32_e64 s[0:1], v56, v50
	v_mov_b32_e32 v44, v65
	s_waitcnt lgkmcnt(0)
	v_mov_b32_e32 v67, v73
	v_cndmask_b32_e64 v52, 0, v43, s[0:1]
	v_cmp_le_i32_e64 s[0:1], v47, v50
	s_nop 1
	v_cndmask_b32_e64 v43, 0, v45, s[0:1]
	v_mov_b32_e32 v45, v71
	v_cmp_le_i32_e64 s[0:1], v56, v50
	v_pk_mul_f32 v[44:45], v[52:53], v[44:45]
	s_nop 0
	v_cndmask_b32_e64 v42, 0, v42, s[0:1]
	v_and_b32_sdwa v63, v44, v221 dst_sel:DWORD dst_unused:UNUSED_PAD src0_sel:WORD_1 src1_sel:DWORD
	v_pk_mul_f32 v[66:67], v[42:43], v[66:67]
	v_and_b32_sdwa v51, v45, v221 dst_sel:DWORD dst_unused:UNUSED_PAD src0_sel:WORD_1 src1_sel:DWORD
	v_add3_u32 v44, v44, v63, s23
	v_add3_u32 v51, v45, v51, s23
	v_and_b32_e32 v75, 0xffff0000, v44
	v_and_b32_sdwa v44, v67, v221 dst_sel:DWORD dst_unused:UNUSED_PAD src0_sel:WORD_1 src1_sel:DWORD
	v_and_b32_sdwa v45, v66, v221 dst_sel:DWORD dst_unused:UNUSED_PAD src0_sel:WORD_1 src1_sel:DWORD
	v_add3_u32 v44, v67, v44, s23
	v_add3_u32 v69, v66, v45, s23
	v_and_b32_e32 v71, 0xffff0000, v44
	v_and_b32_e32 v74, 0xffff0000, v69
	v_mov_b32_e32 v63, v64
	v_mul_f32_e32 v44, v64, v75
	v_pk_fma_f32 v[44:45], v[62:63], v[74:75], v[44:45] op_sel_hi:[1,1,0]
	v_pk_add_f32 v[66:67], v[42:43], v[52:53]
	v_and_b32_e32 v45, 0xffff0000, v51
	v_mul_f32_e32 v62, v70, v45
	v_mov_b32_e32 v45, v53
	v_mov_b32_e32 v63, v43
	v_mul_f32_e32 v64, v72, v71
	v_pk_add_f32 v[42:43], v[44:45], v[62:63]
	v_mov_b32_e32 v65, v66
	v_pk_add_f32 v[42:43], v[64:65], v[42:43]
	v_mov_b32_e32 v112, v42
	v_mov_b32_e32 v113, v43
	v_or_b32_sdwa v53, v71, v51 dst_sel:DWORD dst_unused:UNUSED_PAD src0_sel:DWORD src1_sel:WORD_1
	v_or_b32_sdwa v52, v69, v75 dst_sel:DWORD dst_unused:UNUSED_PAD src0_sel:WORD_1 src1_sel:DWORD
	v_mad_u64_u32 v[62:63], s[0:1], v50, s13, v[48:49]
	ds_write_b64 v62, v[52:53] offset:2048
	v_add_u32_e32 v42, 0x400, v55
	ds_read_b128 v[50:53], v57
	ds_read_b128 v[62:65], v57 offset:16
	v_ashrrev_i32_e32 v42, 5, v42
	v_cmp_ge_i32_e64 s[0:1], v42, v46
	s_waitcnt lgkmcnt(1)
	v_mov_b32_e32 v66, v51
	s_waitcnt vmcnt(5)
	v_cndmask_b32_e64 v45, 0, v40, s[0:1]
	v_cmp_lt_i32_e64 s[0:1], v56, v42
	v_mov_b32_e32 v40, v53
	s_waitcnt lgkmcnt(0)
	v_mov_b32_e32 v67, v65
	v_cndmask_b32_e64 v44, 0, v39, s[0:1]
	v_cmp_le_i32_e64 s[0:1], v47, v42
	s_nop 1
	v_cndmask_b32_e64 v39, 0, v41, s[0:1]
	v_mov_b32_e32 v41, v63
	v_cmp_le_i32_e64 s[0:1], v56, v42
	v_pk_mul_f32 v[40:41], v[44:45], v[40:41]
	s_nop 0
	v_cndmask_b32_e64 v38, 0, v38, s[0:1]
	v_and_b32_sdwa v51, v40, v221 dst_sel:DWORD dst_unused:UNUSED_PAD src0_sel:WORD_1 src1_sel:DWORD
	v_pk_mul_f32 v[66:67], v[38:39], v[66:67]
	v_and_b32_sdwa v43, v41, v221 dst_sel:DWORD dst_unused:UNUSED_PAD src0_sel:WORD_1 src1_sel:DWORD
	v_add3_u32 v40, v40, v51, s23
	v_add3_u32 v43, v41, v43, s23
	v_and_b32_e32 v71, 0xffff0000, v40
	v_and_b32_sdwa v40, v67, v221 dst_sel:DWORD dst_unused:UNUSED_PAD src0_sel:WORD_1 src1_sel:DWORD
	v_and_b32_sdwa v41, v66, v221 dst_sel:DWORD dst_unused:UNUSED_PAD src0_sel:WORD_1 src1_sel:DWORD
	v_add3_u32 v40, v67, v40, s23
	v_add3_u32 v65, v66, v41, s23
	v_and_b32_e32 v66, 0xffff0000, v40
	v_and_b32_e32 v70, 0xffff0000, v65
	v_mov_b32_e32 v51, v52
	v_mul_f32_e32 v40, v52, v71
	v_pk_fma_f32 v[40:41], v[50:51], v[70:71], v[40:41] op_sel_hi:[1,1,0]
	v_mov_b32_e32 v51, v39
	v_and_b32_e32 v41, 0xffff0000, v43
	v_mul_f32_e32 v50, v62, v41
	v_pk_add_f32 v[62:63], v[38:39], v[44:45]
	v_mov_b32_e32 v41, v45
	v_mul_f32_e32 v52, v64, v66
	v_pk_add_f32 v[38:39], v[40:41], v[50:51]
	v_mov_b32_e32 v53, v62
	v_pk_add_f32 v[38:39], v[52:53], v[38:39]
	v_mov_b32_e32 v114, v38
	v_mov_b32_e32 v115, v39
	v_or_b32_sdwa v45, v66, v43 dst_sel:DWORD dst_unused:UNUSED_PAD src0_sel:DWORD src1_sel:WORD_1
	v_or_b32_sdwa v44, v65, v71 dst_sel:DWORD dst_unused:UNUSED_PAD src0_sel:WORD_1 src1_sel:DWORD
	v_mad_u64_u32 v[50:51], s[0:1], v42, s13, v[48:49]
	ds_write_b64 v50, v[44:45] offset:2048
	v_add_u32_e32 v38, 0x600, v55
	s_waitcnt lgkmcnt(0)
	ds_read_b128 v[40:43], v57
	ds_read_b128 v[50:53], v57 offset:16
	v_ashrrev_i32_e32 v38, 5, v38
	v_cmp_ge_i32_e64 s[0:1], v38, v46
	s_waitcnt lgkmcnt(1)
	v_mov_b32_e32 v62, v41
	s_waitcnt vmcnt(4)
	v_cndmask_b32_e64 v45, 0, v36, s[0:1]
	v_cmp_lt_i32_e64 s[0:1], v56, v38
	v_mov_b32_e32 v36, v43
	s_waitcnt lgkmcnt(0)
	v_mov_b32_e32 v63, v53
	v_cndmask_b32_e64 v44, 0, v35, s[0:1]
	v_cmp_le_i32_e64 s[0:1], v47, v38
	s_nop 1
	v_cndmask_b32_e64 v35, 0, v37, s[0:1]
	v_mov_b32_e32 v37, v51
	v_cmp_le_i32_e64 s[0:1], v56, v38
	v_pk_mul_f32 v[36:37], v[44:45], v[36:37]
	s_nop 0
	v_cndmask_b32_e64 v34, 0, v34, s[0:1]
	v_and_b32_sdwa v41, v36, v221 dst_sel:DWORD dst_unused:UNUSED_PAD src0_sel:WORD_1 src1_sel:DWORD
	v_pk_mul_f32 v[62:63], v[34:35], v[62:63]
	v_and_b32_sdwa v39, v37, v221 dst_sel:DWORD dst_unused:UNUSED_PAD src0_sel:WORD_1 src1_sel:DWORD
	v_add3_u32 v36, v36, v41, s23
	v_add3_u32 v39, v37, v39, s23
	v_and_b32_e32 v65, 0xffff0000, v36
	v_and_b32_sdwa v36, v63, v221 dst_sel:DWORD dst_unused:UNUSED_PAD src0_sel:WORD_1 src1_sel:DWORD
	v_and_b32_sdwa v37, v62, v221 dst_sel:DWORD dst_unused:UNUSED_PAD src0_sel:WORD_1 src1_sel:DWORD
	v_add3_u32 v36, v63, v36, s23
	v_add3_u32 v53, v62, v37, s23
	v_and_b32_e32 v62, 0xffff0000, v36
	v_and_b32_e32 v64, 0xffff0000, v53
	v_mov_b32_e32 v41, v42
	v_mul_f32_e32 v36, v42, v65
	v_pk_fma_f32 v[36:37], v[40:41], v[64:65], v[36:37] op_sel_hi:[1,1,0]
	v_mov_b32_e32 v41, v35
	v_and_b32_e32 v37, 0xffff0000, v39
	v_mul_f32_e32 v40, v50, v37
	v_pk_add_f32 v[50:51], v[34:35], v[44:45]
	v_mov_b32_e32 v37, v45
	v_mul_f32_e32 v42, v52, v62
	v_pk_add_f32 v[34:35], v[36:37], v[40:41]
	v_mov_b32_e32 v43, v50
	v_pk_add_f32 v[34:35], v[42:43], v[34:35]
	v_mov_b32_e32 v116, v34
	v_mov_b32_e32 v117, v35
	v_or_b32_sdwa v41, v62, v39 dst_sel:DWORD dst_unused:UNUSED_PAD src0_sel:DWORD src1_sel:WORD_1
	v_or_b32_sdwa v40, v53, v65 dst_sel:DWORD dst_unused:UNUSED_PAD src0_sel:WORD_1 src1_sel:DWORD
	v_mad_u64_u32 v[42:43], s[0:1], v38, s13, v[48:49]
	ds_write_b64 v42, v[40:41] offset:2048
	v_add_u32_e32 v34, 0x800, v55
	s_waitcnt lgkmcnt(0)
	ds_read_b128 v[36:39], v57
	ds_read_b128 v[40:43], v57 offset:16
	v_ashrrev_i32_e32 v34, 5, v34
	v_cmp_ge_i32_e64 s[0:1], v34, v46
	s_waitcnt lgkmcnt(1)
	v_mov_b32_e32 v50, v37
	s_waitcnt vmcnt(3)
	v_cndmask_b32_e64 v45, 0, v32, s[0:1]
	v_cmp_lt_i32_e64 s[0:1], v56, v34
	v_mov_b32_e32 v32, v39
	s_waitcnt lgkmcnt(0)
	v_mov_b32_e32 v51, v43
	v_cndmask_b32_e64 v44, 0, v31, s[0:1]
	v_cmp_le_i32_e64 s[0:1], v47, v34
	s_nop 1
	v_cndmask_b32_e64 v31, 0, v33, s[0:1]
	v_mov_b32_e32 v33, v41
	v_cmp_le_i32_e64 s[0:1], v56, v34
	v_pk_mul_f32 v[32:33], v[44:45], v[32:33]
	s_nop 0
	v_cndmask_b32_e64 v30, 0, v30, s[0:1]
	v_and_b32_sdwa v37, v32, v221 dst_sel:DWORD dst_unused:UNUSED_PAD src0_sel:WORD_1 src1_sel:DWORD
	v_pk_mul_f32 v[50:51], v[30:31], v[50:51]
	v_and_b32_sdwa v35, v33, v221 dst_sel:DWORD dst_unused:UNUSED_PAD src0_sel:WORD_1 src1_sel:DWORD
	v_add3_u32 v32, v32, v37, s23
	v_add3_u32 v35, v33, v35, s23
	v_and_b32_e32 v53, 0xffff0000, v32
	v_and_b32_sdwa v32, v51, v221 dst_sel:DWORD dst_unused:UNUSED_PAD src0_sel:WORD_1 src1_sel:DWORD
	v_and_b32_sdwa v33, v50, v221 dst_sel:DWORD dst_unused:UNUSED_PAD src0_sel:WORD_1 src1_sel:DWORD
	v_add3_u32 v32, v51, v32, s23
	v_add3_u32 v43, v50, v33, s23
	v_and_b32_e32 v50, 0xffff0000, v32
	v_and_b32_e32 v52, 0xffff0000, v43
	v_mov_b32_e32 v37, v38
	v_mul_f32_e32 v32, v38, v53
	v_pk_fma_f32 v[32:33], v[36:37], v[52:53], v[32:33] op_sel_hi:[1,1,0]
	v_mov_b32_e32 v37, v31
	v_and_b32_e32 v33, 0xffff0000, v35
	v_mul_f32_e32 v36, v40, v33
	v_pk_add_f32 v[40:41], v[30:31], v[44:45]
	v_mov_b32_e32 v33, v45
	v_mul_f32_e32 v38, v42, v50
	v_pk_add_f32 v[30:31], v[32:33], v[36:37]
	v_mov_b32_e32 v39, v40
	v_pk_add_f32 v[30:31], v[38:39], v[30:31]
	v_mov_b32_e32 v118, v30
	v_mov_b32_e32 v119, v31
	v_or_b32_sdwa v37, v50, v35 dst_sel:DWORD dst_unused:UNUSED_PAD src0_sel:DWORD src1_sel:WORD_1
	v_or_b32_sdwa v36, v43, v53 dst_sel:DWORD dst_unused:UNUSED_PAD src0_sel:WORD_1 src1_sel:DWORD
	v_mad_u64_u32 v[38:39], s[0:1], v34, s13, v[48:49]
	ds_write_b64 v38, v[36:37] offset:2048
	v_add_u32_e32 v30, 0xa00, v55
	s_waitcnt lgkmcnt(0)
	ds_read_b128 v[32:35], v57
	ds_read_b128 v[36:39], v57 offset:16
	v_ashrrev_i32_e32 v30, 5, v30
	v_cmp_ge_i32_e64 s[0:1], v30, v46
	s_waitcnt lgkmcnt(1)
	v_mov_b32_e32 v42, v33
	s_waitcnt vmcnt(2)
	v_cndmask_b32_e64 v41, 0, v28, s[0:1]
	v_cmp_lt_i32_e64 s[0:1], v56, v30
	v_mov_b32_e32 v28, v35
	s_waitcnt lgkmcnt(0)
	v_mov_b32_e32 v43, v39
	v_cndmask_b32_e64 v40, 0, v27, s[0:1]
	v_cmp_le_i32_e64 s[0:1], v47, v30
	s_nop 1
	v_cndmask_b32_e64 v27, 0, v29, s[0:1]
	v_mov_b32_e32 v29, v37
	v_cmp_le_i32_e64 s[0:1], v56, v30
	v_pk_mul_f32 v[28:29], v[40:41], v[28:29]
	s_nop 0
	v_cndmask_b32_e64 v26, 0, v26, s[0:1]
	v_and_b32_sdwa v33, v28, v221 dst_sel:DWORD dst_unused:UNUSED_PAD src0_sel:WORD_1 src1_sel:DWORD
	v_pk_mul_f32 v[42:43], v[26:27], v[42:43]
	v_and_b32_sdwa v31, v29, v221 dst_sel:DWORD dst_unused:UNUSED_PAD src0_sel:WORD_1 src1_sel:DWORD
	v_add3_u32 v28, v28, v33, s23
	v_add3_u32 v31, v29, v31, s23
	v_and_b32_e32 v45, 0xffff0000, v28
	v_and_b32_sdwa v28, v43, v221 dst_sel:DWORD dst_unused:UNUSED_PAD src0_sel:WORD_1 src1_sel:DWORD
	v_and_b32_sdwa v29, v42, v221 dst_sel:DWORD dst_unused:UNUSED_PAD src0_sel:WORD_1 src1_sel:DWORD
	v_add3_u32 v28, v43, v28, s23
	v_add3_u32 v39, v42, v29, s23
	v_and_b32_e32 v42, 0xffff0000, v28
	v_and_b32_e32 v44, 0xffff0000, v39
	v_mov_b32_e32 v33, v34
	v_mul_f32_e32 v28, v34, v45
	v_pk_fma_f32 v[28:29], v[32:33], v[44:45], v[28:29] op_sel_hi:[1,1,0]
	v_mov_b32_e32 v33, v27
	v_and_b32_e32 v29, 0xffff0000, v31
	v_mul_f32_e32 v32, v36, v29
	v_pk_add_f32 v[36:37], v[26:27], v[40:41]
	v_mov_b32_e32 v29, v41
	v_mul_f32_e32 v34, v38, v42
	v_pk_add_f32 v[26:27], v[28:29], v[32:33]
	v_mov_b32_e32 v35, v36
	v_pk_add_f32 v[26:27], v[34:35], v[26:27]
	v_mov_b32_e32 v120, v26
	v_mov_b32_e32 v121, v27
	v_or_b32_sdwa v33, v42, v31 dst_sel:DWORD dst_unused:UNUSED_PAD src0_sel:DWORD src1_sel:WORD_1
	v_or_b32_sdwa v32, v39, v45 dst_sel:DWORD dst_unused:UNUSED_PAD src0_sel:WORD_1 src1_sel:DWORD
	v_mad_u64_u32 v[34:35], s[0:1], v30, s13, v[48:49]
	ds_write_b64 v34, v[32:33] offset:2048
	v_add_u32_e32 v26, 0xc00, v55
	s_waitcnt lgkmcnt(0)
	ds_read_b128 v[28:31], v57
	ds_read_b128 v[32:35], v57 offset:16
	v_ashrrev_i32_e32 v26, 5, v26
	v_cmp_ge_i32_e64 s[0:1], v26, v46
	s_waitcnt lgkmcnt(1)
	v_mov_b32_e32 v38, v29
	s_waitcnt vmcnt(1)
	v_cndmask_b32_e64 v37, 0, v24, s[0:1]
	v_cmp_lt_i32_e64 s[0:1], v56, v26
	v_mov_b32_e32 v24, v31
	s_waitcnt lgkmcnt(0)
	v_mov_b32_e32 v39, v35
	v_cndmask_b32_e64 v36, 0, v23, s[0:1]
	v_cmp_le_i32_e64 s[0:1], v47, v26
	s_nop 1
	v_cndmask_b32_e64 v23, 0, v25, s[0:1]
	v_mov_b32_e32 v25, v33
	v_cmp_le_i32_e64 s[0:1], v56, v26
	v_pk_mul_f32 v[24:25], v[36:37], v[24:25]
	s_nop 0
	v_cndmask_b32_e64 v22, 0, v22, s[0:1]
	v_and_b32_sdwa v29, v24, v221 dst_sel:DWORD dst_unused:UNUSED_PAD src0_sel:WORD_1 src1_sel:DWORD
	v_pk_mul_f32 v[38:39], v[22:23], v[38:39]
	v_and_b32_sdwa v27, v25, v221 dst_sel:DWORD dst_unused:UNUSED_PAD src0_sel:WORD_1 src1_sel:DWORD
	v_add3_u32 v24, v24, v29, s23
	v_add3_u32 v27, v25, v27, s23
	v_and_b32_e32 v41, 0xffff0000, v24
	v_and_b32_sdwa v24, v39, v221 dst_sel:DWORD dst_unused:UNUSED_PAD src0_sel:WORD_1 src1_sel:DWORD
	v_and_b32_sdwa v25, v38, v221 dst_sel:DWORD dst_unused:UNUSED_PAD src0_sel:WORD_1 src1_sel:DWORD
	v_add3_u32 v24, v39, v24, s23
	v_add3_u32 v35, v38, v25, s23
	v_and_b32_e32 v38, 0xffff0000, v24
	v_and_b32_e32 v40, 0xffff0000, v35
	v_mov_b32_e32 v29, v30
	v_mul_f32_e32 v24, v30, v41
	v_pk_fma_f32 v[24:25], v[28:29], v[40:41], v[24:25] op_sel_hi:[1,1,0]
	v_mov_b32_e32 v29, v23
	v_and_b32_e32 v25, 0xffff0000, v27
	v_mul_f32_e32 v28, v32, v25
	v_pk_add_f32 v[32:33], v[22:23], v[36:37]
	v_mov_b32_e32 v25, v37
	v_mul_f32_e32 v30, v34, v38
	v_pk_add_f32 v[22:23], v[24:25], v[28:29]
	v_mov_b32_e32 v31, v32
	v_pk_add_f32 v[22:23], v[30:31], v[22:23]
	v_mov_b32_e32 v122, v22
	v_mov_b32_e32 v123, v23
	v_or_b32_sdwa v29, v38, v27 dst_sel:DWORD dst_unused:UNUSED_PAD src0_sel:DWORD src1_sel:WORD_1
	v_or_b32_sdwa v28, v35, v41 dst_sel:DWORD dst_unused:UNUSED_PAD src0_sel:WORD_1 src1_sel:DWORD
	v_mad_u64_u32 v[30:31], s[0:1], v26, s13, v[48:49]
	ds_write_b64 v30, v[28:29] offset:2048
	v_add_u32_e32 v22, 0xe00, v55
	s_waitcnt lgkmcnt(0)
	ds_read_b128 v[24:27], v57
	ds_read_b128 v[28:31], v57 offset:16
	v_ashrrev_i32_e32 v22, 5, v22
	v_cmp_ge_i32_e64 s[0:1], v22, v46
	s_waitcnt lgkmcnt(1)
	v_mov_b32_e32 v34, v25
	s_waitcnt vmcnt(0)
	v_cndmask_b32_e64 v33, 0, v20, s[0:1]
	v_cmp_lt_i32_e64 s[0:1], v56, v22
	v_mov_b32_e32 v20, v27
	s_waitcnt lgkmcnt(0)
	v_mov_b32_e32 v35, v31
	v_cndmask_b32_e64 v32, 0, v19, s[0:1]
	v_cmp_le_i32_e64 s[0:1], v47, v22
	s_nop 1
	v_cndmask_b32_e64 v19, 0, v21, s[0:1]
	v_mov_b32_e32 v21, v29
	v_cmp_le_i32_e64 s[0:1], v56, v22
	v_pk_mul_f32 v[20:21], v[32:33], v[20:21]
	s_nop 0
	v_cndmask_b32_e64 v18, 0, v18, s[0:1]
	v_and_b32_sdwa v25, v20, v221 dst_sel:DWORD dst_unused:UNUSED_PAD src0_sel:WORD_1 src1_sel:DWORD
	v_pk_mul_f32 v[34:35], v[18:19], v[34:35]
	v_and_b32_sdwa v23, v21, v221 dst_sel:DWORD dst_unused:UNUSED_PAD src0_sel:WORD_1 src1_sel:DWORD
	v_add3_u32 v20, v20, v25, s23
	v_add3_u32 v23, v21, v23, s23
	v_and_b32_e32 v37, 0xffff0000, v20
	v_and_b32_sdwa v20, v35, v221 dst_sel:DWORD dst_unused:UNUSED_PAD src0_sel:WORD_1 src1_sel:DWORD
	v_and_b32_sdwa v21, v34, v221 dst_sel:DWORD dst_unused:UNUSED_PAD src0_sel:WORD_1 src1_sel:DWORD
	v_add3_u32 v20, v35, v20, s23
	v_add3_u32 v31, v34, v21, s23
	v_and_b32_e32 v34, 0xffff0000, v20
	v_and_b32_e32 v36, 0xffff0000, v31
	v_mov_b32_e32 v25, v26
	v_mul_f32_e32 v20, v26, v37
	v_pk_fma_f32 v[20:21], v[24:25], v[36:37], v[20:21] op_sel_hi:[1,1,0]
	v_mov_b32_e32 v25, v19
	v_and_b32_e32 v21, 0xffff0000, v23
	v_mul_f32_e32 v24, v28, v21
	v_pk_add_f32 v[28:29], v[18:19], v[32:33]
	v_mov_b32_e32 v21, v33
	v_mul_f32_e32 v26, v30, v34
	v_pk_add_f32 v[18:19], v[20:21], v[24:25]
	v_mov_b32_e32 v27, v28
	v_pk_add_f32 v[18:19], v[26:27], v[18:19]
	v_mov_b32_e32 v124, v18
	v_mov_b32_e32 v125, v19
	v_or_b32_sdwa v25, v34, v23 dst_sel:DWORD dst_unused:UNUSED_PAD src0_sel:DWORD src1_sel:WORD_1
	v_or_b32_sdwa v24, v31, v37 dst_sel:DWORD dst_unused:UNUSED_PAD src0_sel:WORD_1 src1_sel:DWORD
	v_mad_u64_u32 v[26:27], s[0:1], v22, s13, v[48:49]
	ds_write_b64 v26, v[24:25] offset:2048
	ds_bpermute_b32 v126, v49, v110
	ds_bpermute_b32 v127, v49, v111
	ds_bpermute_b32 v128, v49, v112
	ds_bpermute_b32 v129, v49, v113
	ds_bpermute_b32 v130, v49, v114
	ds_bpermute_b32 v131, v49, v115
	ds_bpermute_b32 v132, v49, v116
	ds_bpermute_b32 v133, v49, v117
	s_waitcnt lgkmcnt(0)
	v_pk_add_f32 v[110:111], v[110:111], v[126:127]
	v_pk_add_f32 v[112:113], v[112:113], v[128:129]
	v_pk_add_f32 v[114:115], v[114:115], v[130:131]
	v_pk_add_f32 v[116:117], v[116:117], v[132:133]
	ds_bpermute_b32 v134, v49, v118
	ds_bpermute_b32 v135, v49, v119
	ds_bpermute_b32 v136, v49, v120
	ds_bpermute_b32 v137, v49, v121
	ds_bpermute_b32 v138, v49, v122
	ds_bpermute_b32 v139, v49, v123
	ds_bpermute_b32 v140, v49, v124
	ds_bpermute_b32 v141, v49, v125
	s_waitcnt lgkmcnt(0)
	v_pk_add_f32 v[118:119], v[118:119], v[134:135]
	v_pk_add_f32 v[120:121], v[120:121], v[136:137]
	v_pk_add_f32 v[122:123], v[122:123], v[138:139]
	v_pk_add_f32 v[124:125], v[124:125], v[140:141]
	ds_bpermute_b32 v126, v58, v110
	ds_bpermute_b32 v127, v58, v111
	ds_bpermute_b32 v128, v58, v112
	ds_bpermute_b32 v129, v58, v113
	ds_bpermute_b32 v130, v58, v114
	ds_bpermute_b32 v131, v58, v115
	ds_bpermute_b32 v132, v58, v116
	ds_bpermute_b32 v133, v58, v117
	s_waitcnt lgkmcnt(0)
	v_pk_add_f32 v[110:111], v[110:111], v[126:127]
	v_pk_add_f32 v[112:113], v[112:113], v[128:129]
	v_pk_add_f32 v[114:115], v[114:115], v[130:131]
	v_pk_add_f32 v[116:117], v[116:117], v[132:133]
	ds_bpermute_b32 v134, v58, v118
	ds_bpermute_b32 v135, v58, v119
	ds_bpermute_b32 v136, v58, v120
	ds_bpermute_b32 v137, v58, v121
	ds_bpermute_b32 v138, v58, v122
	ds_bpermute_b32 v139, v58, v123
	ds_bpermute_b32 v140, v58, v124
	ds_bpermute_b32 v141, v58, v125
	s_waitcnt lgkmcnt(0)
	v_pk_add_f32 v[118:119], v[118:119], v[134:135]
	v_pk_add_f32 v[120:121], v[120:121], v[136:137]
	v_pk_add_f32 v[122:123], v[122:123], v[138:139]
	v_pk_add_f32 v[124:125], v[124:125], v[140:141]
	ds_bpermute_b32 v126, v59, v110
	ds_bpermute_b32 v127, v59, v111
	ds_bpermute_b32 v128, v59, v112
	ds_bpermute_b32 v129, v59, v113
	ds_bpermute_b32 v130, v59, v114
	ds_bpermute_b32 v131, v59, v115
	ds_bpermute_b32 v132, v59, v116
	ds_bpermute_b32 v133, v59, v117
	s_waitcnt lgkmcnt(0)
	v_pk_add_f32 v[110:111], v[110:111], v[126:127]
	v_pk_add_f32 v[112:113], v[112:113], v[128:129]
	v_pk_add_f32 v[114:115], v[114:115], v[130:131]
	v_pk_add_f32 v[116:117], v[116:117], v[132:133]
	ds_bpermute_b32 v134, v59, v118
	ds_bpermute_b32 v135, v59, v119
	ds_bpermute_b32 v136, v59, v120
	ds_bpermute_b32 v137, v59, v121
	ds_bpermute_b32 v138, v59, v122
	ds_bpermute_b32 v139, v59, v123
	ds_bpermute_b32 v140, v59, v124
	ds_bpermute_b32 v141, v59, v125
	s_waitcnt lgkmcnt(0)
	v_pk_add_f32 v[118:119], v[118:119], v[134:135]
	v_pk_add_f32 v[120:121], v[120:121], v[136:137]
	v_pk_add_f32 v[122:123], v[122:123], v[138:139]
	v_pk_add_f32 v[124:125], v[124:125], v[140:141]
	ds_bpermute_b32 v126, v60, v110
	ds_bpermute_b32 v127, v60, v111
	ds_bpermute_b32 v128, v60, v112
	ds_bpermute_b32 v129, v60, v113
	ds_bpermute_b32 v130, v60, v114
	ds_bpermute_b32 v131, v60, v115
	ds_bpermute_b32 v132, v60, v116
	ds_bpermute_b32 v133, v60, v117
	s_waitcnt lgkmcnt(0)
	v_pk_add_f32 v[110:111], v[110:111], v[126:127]
	v_pk_add_f32 v[112:113], v[112:113], v[128:129]
	v_pk_add_f32 v[114:115], v[114:115], v[130:131]
	v_pk_add_f32 v[116:117], v[116:117], v[132:133]
	ds_bpermute_b32 v134, v60, v118
	ds_bpermute_b32 v135, v60, v119
	ds_bpermute_b32 v136, v60, v120
	ds_bpermute_b32 v137, v60, v121
	ds_bpermute_b32 v138, v60, v122
	ds_bpermute_b32 v139, v60, v123
	ds_bpermute_b32 v140, v60, v124
	ds_bpermute_b32 v141, v60, v125
	s_waitcnt lgkmcnt(0)
	v_pk_add_f32 v[118:119], v[118:119], v[134:135]
	v_pk_add_f32 v[120:121], v[120:121], v[136:137]
	v_pk_add_f32 v[122:123], v[122:123], v[138:139]
	v_pk_add_f32 v[124:125], v[124:125], v[140:141]
	ds_bpermute_b32 v126, v61, v110
	ds_bpermute_b32 v127, v61, v111
	ds_bpermute_b32 v128, v61, v112
	ds_bpermute_b32 v129, v61, v113
	ds_bpermute_b32 v130, v61, v114
	ds_bpermute_b32 v131, v61, v115
	ds_bpermute_b32 v132, v61, v116
	ds_bpermute_b32 v133, v61, v117
	s_waitcnt lgkmcnt(0)
	v_pk_add_f32 v[110:111], v[110:111], v[126:127]
	v_pk_add_f32 v[112:113], v[112:113], v[128:129]
	v_pk_add_f32 v[114:115], v[114:115], v[130:131]
	v_pk_add_f32 v[116:117], v[116:117], v[132:133]
	ds_bpermute_b32 v134, v61, v118
	ds_bpermute_b32 v135, v61, v119
	ds_bpermute_b32 v136, v61, v120
	ds_bpermute_b32 v137, v61, v121
	ds_bpermute_b32 v138, v61, v122
	ds_bpermute_b32 v139, v61, v123
	ds_bpermute_b32 v140, v61, v124
	ds_bpermute_b32 v141, v61, v125
	s_waitcnt lgkmcnt(0)
	v_pk_add_f32 v[118:119], v[118:119], v[134:135]
	v_pk_add_f32 v[120:121], v[120:121], v[136:137]
	v_pk_add_f32 v[122:123], v[122:123], v[138:139]
	v_pk_add_f32 v[124:125], v[124:125], v[140:141]
	v_lshrrev_b32_e32 v142, 5, v200
	v_lshlrev_b32_e32 v142, 3, v142
	s_and_saveexec_b64 s[0:1], vcc
	ds_write_b64 v142, v[110:111] offset:1024
	ds_write_b64 v142, v[112:113] offset:1152
	ds_write_b64 v142, v[114:115] offset:1280
	ds_write_b64 v142, v[116:117] offset:1408
	ds_write_b64 v142, v[118:119] offset:1536
	ds_write_b64 v142, v[120:121] offset:1664
	ds_write_b64 v142, v[122:123] offset:1792
	ds_write_b64 v142, v[124:125] offset:1920
	s_or_b64 exec, exec, s[0:1]
	s_add_i32 s12, s12, s7
	v_or_b32_e32 v72, s6, v68
	s_movk_i32 s0, 0x3500
	v_lshl_or_b32 v18, v54, 2, s12
	s_waitcnt lgkmcnt(1)
	v_mul_lo_u32 v20, v72, s0
	v_readlane_b32 s0, v252, 53
	v_ashrrev_i32_e32 v19, 31, v18
	s_waitcnt lgkmcnt(0)
	v_mov_b32_e32 v21, v1
	v_readlane_b32 s1, v252, 54
	v_lshlrev_b64 v[66:67], 1, v[18:19]
	v_readlane_b32 s40, v250, 6
	v_lshl_add_u64 v[20:21], v[20:21], 1, s[0:1]
	v_lshl_add_u64 v[20:21], v[20:21], 0, v[66:67]
	v_add_co_u32_e32 v22, vcc, 0x1000, v20
	s_lshl_b64 s[0:1], s[76:77], 9
	s_nop 0
	v_addc_co_u32_e32 v23, vcc, 0, v21, vcc
	global_load_dwordx2 v[62:63], v[22:23], off
	v_add_co_u32_e32 v22, vcc, 0x2000, v20
	v_readlane_b32 s41, v250, 7
	s_nop 0
	v_addc_co_u32_e32 v23, vcc, 0, v21, vcc
	global_load_dwordx2 v[64:65], v[22:23], off
	v_add_co_u32_e32 v22, vcc, 0x6b000, v20
	s_add_u32 s0, s40, s0
	s_nop 0
	v_addc_co_u32_e32 v23, vcc, 0, v21, vcc
	global_load_dwordx2 v[58:59], v[22:23], off
	v_add_co_u32_e32 v22, vcc, 0x6c000, v20
	v_mul_u32_u24_e32 v26, 0x110, v68
	s_nop 0
	v_addc_co_u32_e32 v23, vcc, 0, v21, vcc
	global_load_dwordx2 v[60:61], v[22:23], off
	v_add_co_u32_e32 v22, vcc, 0xd5000, v20
	s_addc_u32 s1, s41, s1
	s_nop 0
	v_addc_co_u32_e32 v23, vcc, 0, v21, vcc
	global_load_dwordx2 v[54:55], v[22:23], off
	v_add_co_u32_e32 v22, vcc, 0xd6000, v20
	v_add3_u32 v0, 0, v0, v26
	s_nop 0
	v_addc_co_u32_e32 v23, vcc, 0, v21, vcc
	global_load_dwordx2 v[56:57], v[22:23], off
	v_add_co_u32_e32 v22, vcc, 0x13f000, v20
	v_or_b32_e32 v106, 16, v68
	s_nop 0
	v_addc_co_u32_e32 v23, vcc, 0, v21, vcc
	global_load_dwordx2 v[50:51], v[22:23], off
	v_add_co_u32_e32 v22, vcc, 0x140000, v20
	v_or_b32_e32 v107, 32, v68
	s_nop 0
	v_addc_co_u32_e32 v23, vcc, 0, v21, vcc
	global_load_dwordx2 v[52:53], v[22:23], off
	v_add_co_u32_e32 v22, vcc, 0x1a9000, v20
	v_or_b32_e32 v108, 48, v68
	s_nop 0
	v_addc_co_u32_e32 v23, vcc, 0, v21, vcc
	global_load_dwordx2 v[46:47], v[22:23], off
	v_add_co_u32_e32 v22, vcc, 0x1aa000, v20
	v_or_b32_e32 v109, 64, v68
	s_nop 0
	v_addc_co_u32_e32 v23, vcc, 0, v21, vcc
	global_load_dwordx2 v[48:49], v[22:23], off
	v_add_co_u32_e32 v22, vcc, 0x213000, v20
	v_readlane_b32 s42, v250, 8
	s_nop 0
	v_addc_co_u32_e32 v23, vcc, 0, v21, vcc
	global_load_dwordx2 v[42:43], v[22:23], off
	v_add_co_u32_e32 v22, vcc, 0x214000, v20
	v_readlane_b32 s43, v250, 9
	s_nop 0
	v_addc_co_u32_e32 v23, vcc, 0, v21, vcc
	global_load_dwordx2 v[44:45], v[22:23], off
	v_add_co_u32_e32 v22, vcc, 0x27d000, v20
	s_nop 1
	v_addc_co_u32_e32 v23, vcc, 0, v21, vcc
	global_load_dwordx2 v[38:39], v[22:23], off
	v_add_co_u32_e32 v22, vcc, 0x27e000, v20
	s_nop 1
	v_addc_co_u32_e32 v23, vcc, 0, v21, vcc
	global_load_dwordx2 v[40:41], v[22:23], off
	v_add_co_u32_e32 v22, vcc, 0x2e7000, v20
	s_nop 1
	v_addc_co_u32_e32 v23, vcc, 0, v21, vcc
	v_add_co_u32_e32 v20, vcc, 0x2e8000, v20
	global_load_dwordx2 v[34:35], v[22:23], off
	s_nop 0
	v_addc_co_u32_e32 v21, vcc, 0, v21, vcc
	global_load_dwordx2 v[36:37], v[20:21], off
	v_lshlrev_b64 v[22:23], 2, v[18:19]
	v_lshlrev_b32_e32 v20, 2, v68
	v_lshl_add_u64 v[18:19], s[8:9], 0, v[22:23]
	v_lshl_add_u64 v[22:23], s[10:11], 0, v[22:23]
	global_load_dword v104, v20, s[0:1]
	global_load_dword v105, v20, s[0:1] offset:64
	global_load_dword v75, v20, s[0:1] offset:128
	global_load_dword v74, v20, s[0:1] offset:192
	global_load_dword v73, v20, s[0:1] offset:256
	global_load_dword v71, v20, s[0:1] offset:320
	global_load_dword v70, v20, s[0:1] offset:384
	global_load_dword v69, v20, s[0:1] offset:448
	v_readlane_b32 s0, v252, 55
	global_load_dwordx4 v[18:21], v[18:19], off
	v_readlane_b32 s1, v252, 56
	global_load_dwordx4 v[22:25], v[22:23], off
	s_barrier
	ds_read_b128 v[26:29], v0 offset:2048
	ds_read_b128 v[30:33], v0 offset:6400
	ds_read_b128 v[76:79], v0 offset:10752
	ds_read_b128 v[80:83], v0 offset:15104
	ds_read_b128 v[84:87], v0 offset:19456
	ds_read_b128 v[88:91], v0 offset:23808
	ds_read_b128 v[92:95], v0 offset:28160
	ds_read_b128 v[96:99], v0 offset:32512
	s_waitcnt lgkmcnt(7)
	v_mfma_f32_16x16x32_bf16 v[26:29], v[14:17], v[26:29], 0
	v_lshl_add_u64 v[66:67], s[0:1], 0, v[66:67]
	s_mov_b64 s[0:1], 0
	s_waitcnt lgkmcnt(6)
	v_mfma_f32_16x16x32_bf16 v[30:33], v[14:17], v[30:33], 0
	s_waitcnt lgkmcnt(5)
	v_mfma_f32_16x16x32_bf16 v[76:79], v[14:17], v[76:79], 0
	s_waitcnt lgkmcnt(4)
	v_mfma_f32_16x16x32_bf16 v[80:83], v[14:17], v[80:83], 0
	s_waitcnt lgkmcnt(3)
	v_mfma_f32_16x16x32_bf16 v[84:87], v[14:17], v[84:87], 0
	s_waitcnt lgkmcnt(2)
	v_mfma_f32_16x16x32_bf16 v[88:91], v[14:17], v[88:91], 0
	s_waitcnt lgkmcnt(1)
	v_mfma_f32_16x16x32_bf16 v[92:95], v[14:17], v[92:95], 0
	s_waitcnt lgkmcnt(0)
	v_mfma_f32_16x16x32_bf16 v[14:17], v[14:17], v[96:99], 0
	ds_read_b128 v[96:99], v0 offset:2112
	s_waitcnt lgkmcnt(0)
	v_mfma_f32_16x16x32_bf16 v[26:29], v[10:13], v[96:99], v[26:29]
	ds_read_b128 v[96:99], v0 offset:6464
	s_waitcnt lgkmcnt(0)
	v_mfma_f32_16x16x32_bf16 v[30:33], v[10:13], v[96:99], v[30:33]
	ds_read_b128 v[96:99], v0 offset:10816
	s_waitcnt lgkmcnt(0)
	v_mfma_f32_16x16x32_bf16 v[76:79], v[10:13], v[96:99], v[76:79]
	ds_read_b128 v[96:99], v0 offset:15168
	s_waitcnt lgkmcnt(0)
	v_mfma_f32_16x16x32_bf16 v[80:83], v[10:13], v[96:99], v[80:83]
	ds_read_b128 v[96:99], v0 offset:19520
	s_waitcnt lgkmcnt(0)
	v_mfma_f32_16x16x32_bf16 v[84:87], v[10:13], v[96:99], v[84:87]
	ds_read_b128 v[96:99], v0 offset:23872
	s_waitcnt lgkmcnt(0)
	v_mfma_f32_16x16x32_bf16 v[88:91], v[10:13], v[96:99], v[88:91]
	ds_read_b128 v[96:99], v0 offset:28224
	s_waitcnt lgkmcnt(0)
	v_mfma_f32_16x16x32_bf16 v[92:95], v[10:13], v[96:99], v[92:95]
	ds_read_b128 v[96:99], v0 offset:32576
	s_waitcnt lgkmcnt(0)
	v_mfma_f32_16x16x32_bf16 v[10:13], v[10:13], v[96:99], v[14:17]
	s_nop 2
	ds_read_b128 v[14:17], v0 offset:2176
	s_waitcnt lgkmcnt(0)
	v_mfma_f32_16x16x32_bf16 v[14:17], v[6:9], v[14:17], v[26:29]
	s_nop 2
	ds_read_b128 v[26:29], v0 offset:6528
	s_waitcnt lgkmcnt(0)
	v_mfma_f32_16x16x32_bf16 v[26:29], v[6:9], v[26:29], v[30:33]
	s_nop 2
	ds_read_b128 v[30:33], v0 offset:10880
	s_waitcnt lgkmcnt(0)
	v_mfma_f32_16x16x32_bf16 v[30:33], v[6:9], v[30:33], v[76:79]
	s_nop 2
	ds_read_b128 v[76:79], v0 offset:15232
	s_waitcnt lgkmcnt(0)
	v_mfma_f32_16x16x32_bf16 v[76:79], v[6:9], v[76:79], v[80:83]
	s_nop 2
	ds_read_b128 v[80:83], v0 offset:19584
	s_waitcnt lgkmcnt(0)
	v_mfma_f32_16x16x32_bf16 v[80:83], v[6:9], v[80:83], v[84:87]
	s_nop 2
	ds_read_b128 v[84:87], v0 offset:23936
	s_waitcnt lgkmcnt(0)
	v_mfma_f32_16x16x32_bf16 v[84:87], v[6:9], v[84:87], v[88:91]
	s_nop 2
	ds_read_b128 v[88:91], v0 offset:28288
	s_waitcnt lgkmcnt(0)
	v_mfma_f32_16x16x32_bf16 v[88:91], v[6:9], v[88:91], v[92:95]
	s_nop 2
	ds_read_b128 v[92:95], v0 offset:32640
	s_waitcnt lgkmcnt(0)
	v_mfma_f32_16x16x32_bf16 v[92:95], v[6:9], v[92:95], v[10:13]
	ds_read_b128 v[6:9], v0 offset:2240
	s_waitcnt lgkmcnt(0)
	v_mfma_f32_16x16x32_bf16 v[96:99], v[2:5], v[6:9], v[14:17]
	ds_read_b128 v[6:9], v0 offset:6592
	s_waitcnt lgkmcnt(0)
	v_mfma_f32_16x16x32_bf16 v[100:103], v[2:5], v[6:9], v[26:29]
	ds_read_b128 v[6:9], v0 offset:10944
	s_waitcnt lgkmcnt(0)
	v_mfma_f32_16x16x32_bf16 v[30:33], v[2:5], v[6:9], v[30:33]
	ds_read_b128 v[6:9], v0 offset:15296
	ds_read_b128 v[10:13], v0 offset:19648
	s_waitcnt lgkmcnt(1)
	v_mfma_f32_16x16x32_bf16 v[26:29], v[2:5], v[6:9], v[76:79]
	ds_read_b128 v[6:9], v0 offset:24000
	s_nop 1
	ds_read_b128 v[76:79], v0 offset:28352
	s_waitcnt lgkmcnt(2)
	v_mfma_f32_16x16x32_bf16 v[14:17], v[2:5], v[10:13], v[80:83]
	s_nop 2
	ds_read_b128 v[80:83], v0 offset:32704
	v_lshl_add_u32 v0, v68, 3, 0
	s_waitcnt lgkmcnt(2)
	v_mfma_f32_16x16x32_bf16 v[10:13], v[2:5], v[6:9], v[84:87]
	s_waitcnt lgkmcnt(1)
	v_mfma_f32_16x16x32_bf16 v[6:9], v[2:5], v[76:79], v[88:91]
	ds_read_b64 v[76:77], v0 offset:1024
	s_waitcnt vmcnt(25)
	v_lshlrev_b32_e32 v0, 16, v62
	v_and_b32_e32 v62, 0xffff0000, v62
	v_or_b32_e32 v84, 0x50, v68
	v_or_b32_e32 v85, 0x60, v68
	s_waitcnt lgkmcnt(0)
	v_sub_f32_e32 v78, v96, v76
	s_waitcnt vmcnt(0)
	v_mul_f32_e32 v79, v22, v77
	v_fmac_f32_e32 v79, v18, v78
	v_add_f32_e32 v78, v104, v79
	v_mul_f32_e32 v0, v78, v0
	v_lshlrev_b32_e32 v78, 16, v64
	v_mul_f32_e32 v0, v0, v78
	v_sub_f32_e32 v78, v97, v76
	v_mul_f32_e32 v79, v23, v77
	v_fmac_f32_e32 v79, v19, v78
	v_add_f32_e32 v78, v104, v79
	v_mul_f32_e32 v62, v78, v62
	v_sub_f32_e32 v78, v98, v76
	v_mul_f32_e32 v79, v24, v77
	v_sub_f32_e32 v76, v99, v76
	v_mul_f32_e32 v77, v25, v77
	v_and_b32_e32 v64, 0xffff0000, v64
	v_fmac_f32_e32 v79, v20, v78
	v_fmac_f32_e32 v77, v21, v76
	v_mul_f32_e32 v62, v62, v64
	v_lshlrev_b32_e32 v64, 16, v63
	v_add_f32_e32 v78, v104, v79
	v_and_b32_e32 v63, 0xffff0000, v63
	v_add_f32_e32 v76, v104, v77
	v_mul_f32_e32 v64, v78, v64
	v_lshlrev_b32_e32 v78, 16, v65
	v_mul_f32_e32 v63, v76, v63
	v_and_b32_e32 v65, 0xffff0000, v65
	v_mul_f32_e32 v64, v64, v78
	v_mul_f32_e32 v63, v63, v65
	v_cvt_pk_bf16_f32 v62, v0, v62
	v_lshl_add_u32 v0, v106, 3, 0
	v_cvt_pk_bf16_f32 v63, v64, v63
	ds_read_b64 v[64:65], v0 offset:1024
	v_lshlrev_b32_e32 v0, 11, v72
	v_lshl_add_u64 v[76:77], v[66:67], 0, v[0:1]
	global_store_dwordx2 v[76:77], v[62:63], off
	v_lshlrev_b32_e32 v0, 16, v58
	s_waitcnt lgkmcnt(0)
	v_sub_f32_e32 v62, v100, v64
	v_mul_f32_e32 v63, v22, v65
	v_fmac_f32_e32 v63, v18, v62
	v_add_f32_e32 v62, v105, v63
	v_mul_f32_e32 v0, v62, v0
	v_lshlrev_b32_e32 v62, 16, v60
	v_mul_f32_e32 v0, v0, v62
	v_sub_f32_e32 v62, v101, v64
	v_mul_f32_e32 v63, v23, v65
	v_fmac_f32_e32 v63, v19, v62
	v_and_b32_e32 v58, 0xffff0000, v58
	v_add_f32_e32 v62, v105, v63
	v_mul_f32_e32 v58, v62, v58
	v_sub_f32_e32 v62, v102, v64
	v_mul_f32_e32 v63, v24, v65
	v_and_b32_e32 v60, 0xffff0000, v60
	v_fmac_f32_e32 v63, v20, v62
	v_mul_f32_e32 v58, v58, v60
	v_lshlrev_b32_e32 v60, 16, v59
	v_add_f32_e32 v62, v105, v63
	v_mul_f32_e32 v60, v62, v60
	v_lshlrev_b32_e32 v62, 16, v61
	v_mul_f32_e32 v60, v60, v62
	v_sub_f32_e32 v62, v103, v64
	v_mul_f32_e32 v63, v25, v65
	v_fmac_f32_e32 v63, v21, v62
	v_and_b32_e32 v59, 0xffff0000, v59
	v_add_f32_e32 v62, v105, v63
	v_mul_f32_e32 v59, v62, v59
	v_and_b32_e32 v61, 0xffff0000, v61
	v_mul_f32_e32 v59, v59, v61
	v_cvt_pk_bf16_f32 v58, v0, v58
	v_cvt_pk_bf16_f32 v59, v60, v59
	v_lshl_add_u32 v60, v107, 3, 0
	ds_read_b64 v[60:61], v60 offset:1024
	v_or_b32_e32 v0, s6, v106
	v_lshlrev_b32_e32 v0, 11, v0
	v_lshl_add_u64 v[62:63], v[66:67], 0, v[0:1]
	global_store_dwordx2 v[62:63], v[58:59], off
	s_waitcnt lgkmcnt(0)
	v_sub_f32_e32 v30, v30, v60
	v_mul_f32_e32 v58, v22, v61
	v_fmac_f32_e32 v58, v18, v30
	v_lshlrev_b32_e32 v0, 16, v54
	v_add_f32_e32 v30, v75, v58
	v_mul_f32_e32 v0, v30, v0
	v_lshlrev_b32_e32 v30, 16, v56
	v_mul_f32_e32 v0, v0, v30
	v_and_b32_e32 v30, 0xffff0000, v54
	v_sub_f32_e32 v31, v31, v60
	v_mul_f32_e32 v54, v23, v61
	v_fmac_f32_e32 v54, v19, v31
	v_add_f32_e32 v31, v75, v54
	v_sub_f32_e32 v32, v32, v60
	v_mul_f32_e32 v54, v24, v61
	v_mul_f32_e32 v30, v31, v30
	v_and_b32_e32 v31, 0xffff0000, v56
	v_fmac_f32_e32 v54, v20, v32
	v_mul_f32_e32 v30, v30, v31
	v_lshlrev_b32_e32 v31, 16, v55
	v_add_f32_e32 v32, v75, v54
	v_sub_f32_e32 v33, v33, v60
	v_mul_f32_e32 v54, v25, v61
	v_mul_f32_e32 v31, v32, v31
	v_lshlrev_b32_e32 v32, 16, v57
	v_fmac_f32_e32 v54, v21, v33
	v_mul_f32_e32 v31, v31, v32
	v_and_b32_e32 v32, 0xffff0000, v55
	v_add_f32_e32 v33, v75, v54
	v_mul_f32_e32 v32, v33, v32
	v_and_b32_e32 v33, 0xffff0000, v57
	v_mul_f32_e32 v32, v32, v33
	v_cvt_pk_bf16_f32 v30, v0, v30
	v_cvt_pk_bf16_f32 v31, v31, v32
	v_lshl_add_u32 v32, v108, 3, 0
	ds_read_b64 v[32:33], v32 offset:1024
	v_or_b32_e32 v0, s6, v107
	v_lshlrev_b32_e32 v0, 11, v0
	v_lshl_add_u64 v[54:55], v[66:67], 0, v[0:1]
	global_store_dwordx2 v[54:55], v[30:31], off
	s_waitcnt lgkmcnt(0)
	v_sub_f32_e32 v26, v26, v32
	v_mul_f32_e32 v30, v22, v33
	v_fmac_f32_e32 v30, v18, v26
	v_lshlrev_b32_e32 v0, 16, v50
	v_add_f32_e32 v26, v74, v30
	v_sub_f32_e32 v27, v27, v32
	v_mul_f32_e32 v30, v23, v33
	v_mul_f32_e32 v0, v26, v0
	v_lshlrev_b32_e32 v26, 16, v52
	v_fmac_f32_e32 v30, v19, v27
	v_mul_f32_e32 v0, v0, v26
	v_and_b32_e32 v26, 0xffff0000, v50
	v_add_f32_e32 v27, v74, v30
	v_sub_f32_e32 v28, v28, v32
	v_mul_f32_e32 v30, v24, v33
	v_mul_f32_e32 v26, v27, v26
	v_and_b32_e32 v27, 0xffff0000, v52
	v_fmac_f32_e32 v30, v20, v28
	v_mul_f32_e32 v26, v26, v27
	v_lshlrev_b32_e32 v27, 16, v51
	v_add_f32_e32 v28, v74, v30
	v_sub_f32_e32 v29, v29, v32
	v_mul_f32_e32 v30, v25, v33
	v_mul_f32_e32 v27, v28, v27
	v_lshlrev_b32_e32 v28, 16, v53
	v_fmac_f32_e32 v30, v21, v29
	v_mul_f32_e32 v27, v27, v28
	v_and_b32_e32 v28, 0xffff0000, v51
	v_add_f32_e32 v29, v74, v30
	v_mul_f32_e32 v28, v29, v28
	v_and_b32_e32 v29, 0xffff0000, v53
	v_mul_f32_e32 v28, v28, v29
	v_cvt_pk_bf16_f32 v26, v0, v26
	v_cvt_pk_bf16_f32 v27, v27, v28
	v_lshl_add_u32 v28, v109, 3, 0
	ds_read_b64 v[28:29], v28 offset:1024
	v_or_b32_e32 v0, s6, v108
	v_lshlrev_b32_e32 v0, 11, v0
	v_lshl_add_u64 v[30:31], v[66:67], 0, v[0:1]
	global_store_dwordx2 v[30:31], v[26:27], off
	s_waitcnt lgkmcnt(0)
	v_sub_f32_e32 v14, v14, v28
	v_mul_f32_e32 v26, v22, v29
	v_fmac_f32_e32 v26, v18, v14
	v_lshlrev_b32_e32 v0, 16, v46
	v_add_f32_e32 v14, v73, v26
	v_sub_f32_e32 v15, v15, v28
	v_mul_f32_e32 v26, v23, v29
	v_mul_f32_e32 v0, v14, v0
	v_lshlrev_b32_e32 v14, 16, v48
	v_fmac_f32_e32 v26, v19, v15
	v_mul_f32_e32 v0, v0, v14
	v_and_b32_e32 v14, 0xffff0000, v46
	v_add_f32_e32 v15, v73, v26
	v_sub_f32_e32 v16, v16, v28
	v_mul_f32_e32 v26, v24, v29
	v_mul_f32_e32 v14, v15, v14
	v_and_b32_e32 v15, 0xffff0000, v48
	v_fmac_f32_e32 v26, v20, v16
	v_mul_f32_e32 v14, v14, v15
	v_lshlrev_b32_e32 v15, 16, v47
	v_add_f32_e32 v16, v73, v26
	v_sub_f32_e32 v17, v17, v28
	v_mul_f32_e32 v26, v25, v29
	v_mul_f32_e32 v15, v16, v15
	v_lshlrev_b32_e32 v16, 16, v49
	v_fmac_f32_e32 v26, v21, v17
	v_mul_f32_e32 v15, v15, v16
	v_and_b32_e32 v16, 0xffff0000, v47
	v_add_f32_e32 v17, v73, v26
	v_mul_f32_e32 v16, v17, v16
	v_and_b32_e32 v17, 0xffff0000, v49
	v_mul_f32_e32 v16, v16, v17
	v_cvt_pk_bf16_f32 v14, v0, v14
	v_cvt_pk_bf16_f32 v15, v15, v16
	v_lshl_add_u32 v16, v84, 3, 0
	ds_read_b64 v[16:17], v16 offset:1024
	v_or_b32_e32 v0, s6, v109
	v_lshlrev_b32_e32 v0, 11, v0
	v_lshl_add_u64 v[26:27], v[66:67], 0, v[0:1]
	global_store_dwordx2 v[26:27], v[14:15], off
	s_waitcnt lgkmcnt(0)
	v_sub_f32_e32 v10, v10, v16
	v_mul_f32_e32 v14, v22, v17
	v_fmac_f32_e32 v14, v18, v10
	v_lshlrev_b32_e32 v0, 16, v42
	v_add_f32_e32 v10, v71, v14
	v_sub_f32_e32 v11, v11, v16
	v_mul_f32_e32 v14, v23, v17
	v_mul_f32_e32 v0, v10, v0
	v_lshlrev_b32_e32 v10, 16, v44
	v_fmac_f32_e32 v14, v19, v11
	v_mul_f32_e32 v0, v0, v10
	v_and_b32_e32 v10, 0xffff0000, v42
	v_add_f32_e32 v11, v71, v14
	v_sub_f32_e32 v12, v12, v16
	v_mul_f32_e32 v14, v24, v17
	v_mul_f32_e32 v10, v11, v10
	v_and_b32_e32 v11, 0xffff0000, v44
	v_fmac_f32_e32 v14, v20, v12
	v_mul_f32_e32 v10, v10, v11
	v_lshlrev_b32_e32 v11, 16, v43
	v_add_f32_e32 v12, v71, v14
	v_sub_f32_e32 v13, v13, v16
	v_mul_f32_e32 v14, v25, v17
	v_mul_f32_e32 v11, v12, v11
	v_lshlrev_b32_e32 v12, 16, v45
	v_fmac_f32_e32 v14, v21, v13
	v_mul_f32_e32 v11, v11, v12
	v_and_b32_e32 v12, 0xffff0000, v43
	v_add_f32_e32 v13, v71, v14
	v_mul_f32_e32 v12, v13, v12
	v_and_b32_e32 v13, 0xffff0000, v45
	v_mul_f32_e32 v12, v12, v13
	v_cvt_pk_bf16_f32 v10, v0, v10
	v_cvt_pk_bf16_f32 v11, v11, v12
	v_lshl_add_u32 v12, v85, 3, 0
	ds_read_b64 v[12:13], v12 offset:1024
	v_or_b32_e32 v0, s6, v84
	v_lshlrev_b32_e32 v0, 11, v0
	v_lshl_add_u64 v[14:15], v[66:67], 0, v[0:1]
	global_store_dwordx2 v[14:15], v[10:11], off
	s_waitcnt lgkmcnt(0)
	v_sub_f32_e32 v6, v6, v12
	v_mul_f32_e32 v10, v22, v13
	v_fmac_f32_e32 v10, v18, v6
	v_lshlrev_b32_e32 v0, 16, v38
	v_add_f32_e32 v6, v70, v10
	v_sub_f32_e32 v7, v7, v12
	v_mul_f32_e32 v10, v23, v13
	v_mul_f32_e32 v0, v6, v0
	v_lshlrev_b32_e32 v6, 16, v40
	v_fmac_f32_e32 v10, v19, v7
	v_mul_f32_e32 v0, v0, v6
	v_and_b32_e32 v6, 0xffff0000, v38
	v_add_f32_e32 v7, v70, v10
	v_sub_f32_e32 v8, v8, v12
	v_mul_f32_e32 v10, v24, v13
	v_mul_f32_e32 v6, v7, v6
	v_and_b32_e32 v7, 0xffff0000, v40
	v_fmac_f32_e32 v10, v20, v8
	v_mul_f32_e32 v6, v6, v7
	v_lshlrev_b32_e32 v7, 16, v39
	v_add_f32_e32 v8, v70, v10
	v_sub_f32_e32 v9, v9, v12
	v_mul_f32_e32 v10, v25, v13
	v_mul_f32_e32 v7, v8, v7
	v_lshlrev_b32_e32 v8, 16, v41
	v_fmac_f32_e32 v10, v21, v9
	v_mul_f32_e32 v7, v7, v8
	v_and_b32_e32 v8, 0xffff0000, v39
	v_add_f32_e32 v9, v70, v10
	v_mul_f32_e32 v8, v9, v8
	v_and_b32_e32 v9, 0xffff0000, v41
	v_or_b32_e32 v68, 0x70, v68
	v_mul_f32_e32 v8, v8, v9
	v_cvt_pk_bf16_f32 v6, v0, v6
	v_cvt_pk_bf16_f32 v7, v7, v8
	v_lshl_add_u32 v8, v68, 3, 0
	ds_read_b64 v[8:9], v8 offset:1024
	v_mfma_f32_16x16x32_bf16 v[2:5], v[2:5], v[80:83], v[92:95]
	v_or_b32_e32 v0, s6, v85
	v_lshlrev_b32_e32 v0, 11, v0
	v_lshl_add_u64 v[10:11], v[66:67], 0, v[0:1]
	global_store_dwordx2 v[10:11], v[6:7], off
	s_waitcnt lgkmcnt(0)
	v_mul_f32_e32 v6, v22, v9
	s_nop 1
	v_sub_f32_e32 v2, v2, v8
	v_fmac_f32_e32 v6, v18, v2
	v_lshlrev_b32_e32 v0, 16, v34
	v_add_f32_e32 v2, v69, v6
	v_sub_f32_e32 v3, v3, v8
	v_mul_f32_e32 v6, v23, v9
	v_mul_f32_e32 v0, v2, v0
	v_lshlrev_b32_e32 v2, 16, v36
	v_fmac_f32_e32 v6, v19, v3
	v_mul_f32_e32 v0, v0, v2
	v_and_b32_e32 v2, 0xffff0000, v34
	v_add_f32_e32 v3, v69, v6
	v_sub_f32_e32 v4, v4, v8
	v_mul_f32_e32 v6, v24, v9
	v_mul_f32_e32 v2, v3, v2
	v_and_b32_e32 v3, 0xffff0000, v36
	v_fmac_f32_e32 v6, v20, v4
	v_mul_f32_e32 v2, v2, v3
	v_lshlrev_b32_e32 v3, 16, v35
	v_add_f32_e32 v4, v69, v6
	v_sub_f32_e32 v5, v5, v8
	v_mul_f32_e32 v6, v25, v9
	v_mul_f32_e32 v3, v4, v3
	v_lshlrev_b32_e32 v4, 16, v37
	v_fmac_f32_e32 v6, v21, v5
	v_mul_f32_e32 v3, v3, v4
	v_and_b32_e32 v4, 0xffff0000, v35
	v_add_f32_e32 v5, v69, v6
	v_mul_f32_e32 v4, v5, v4
	v_and_b32_e32 v5, 0xffff0000, v37
	v_cvt_pk_bf16_f32 v2, v0, v2
	v_or_b32_e32 v0, s6, v68
	v_mul_f32_e32 v4, v4, v5
	v_lshlrev_b32_e32 v0, 11, v0
	v_cvt_pk_bf16_f32 v3, v3, v4
	v_lshl_add_u64 v[4:5], v[66:67], 0, v[0:1]
	global_store_dwordx2 v[4:5], v[2:3], off
	s_barrier
